# attention: K and V LDS fragment reads rotate through spare register quads with counted lgkmcnt waits instead of a full wait before every MFMA
# speedup vs baseline: 1.0036x; 1.0036x over previous
; #define LAS __attribute__((address_space(3)))
; __device__ __forceinline__ void attn_unit(int b, int h, int qb, const bf16_t* __restrict__ QK, const bf16_t* __restrict__ VT, bf16_t* __restrict__ O, const float* __restrict__ qg, const float* __restrict__ kg, ...
;     ...
;             const LAS unsigned char* kb_ = Kb + buf * AK_BUF + kfo; const LAS unsigned char* vb_ = Vb + buf * AV_BUF + vfo;
;             f32x16 p[2];
; #pragma unroll
;             for (int kb = 0; kb < 2; ++kb) {
; #pragma unroll
;                 for (int r = 0; r < 16; ++r) p[kb][r] = 0.f;
; #pragma unroll
;                 for (int ks = 0; ks < 8; ++ks) { const bf16x8 a = *(const LAS bf16x8*)(kb_ + kb * 32 * AK_ROWB + ks * 32); p[kb] = __builtin_amdgcn_mfma_f32_32x32x16_bf16(a, qr[ks], p[kb], 0, 0, 0); }
;             }
;             const bool needmask = (kt * 64 + 63 >= q0 + wid * 32);
;             float T[2];
; #pragma unroll
;     ...
;                 float run = 0.f; const int s0 = kt * 64 + kb * 32 + hi * 16;
; #pragma unroll
;                 for (int r = 15; r >= 0; --r) {
;                     const float z = p[kb][r];
;                     const float e = __builtin_amdgcn_exp2f(z);
;                     float sp = __builtin_amdgcn_logf(1.0f + e);
;                     float a = __builtin_amdgcn_exp2f(z - sp - run);
;                     if (needmask && !(s0 + r < tq)) { sp = 0.f; a = 0.f; }
;                     run += sp; p[kb][r] = a; }
.LBB0_467:
	s_xor_b64 s[16:17], s[16:17], -1
	s_andn2_b64 vcc, exec, s[16:17]
	s_mov_b64 s[16:17], -1
	s_cbranch_vccnz .LBB0_470
	s_add_i32 s3, s18, 64
	s_cmp_ge_i32 s3, s13
	s_mov_b64 s[16:17], 0
	s_cbranch_scc1 .LBB0_470
	s_mul_i32 s3, s26, 0x4400
	v_add_u32_e32 v175, s3, v190
	ds_read_b128 v[64:67], v175
	ds_read_b128 v[80:83], v175 offset:32
	ds_read_b128 v[84:87], v175 offset:64
	ds_read_b128 v[88:91], v175 offset:96
	ds_read_b128 v[92:95], v175 offset:128
	s_add_i32 s3, s18, 0x7f
	s_cmp_lt_i32 s3, s23
	s_cselect_b64 s[62:63], -1, 0
	s_waitcnt lgkmcnt(4)
	v_mfma_f32_32x32x16_bf16 v[64:79], v[64:67], v[106:109], 0
	s_mul_i32 s16, s26, 0x4800
	ds_read_b128 v[194:197], v175 offset:8736
	s_waitcnt lgkmcnt(4)
	v_mfma_f32_32x32x16_bf16 v[64:79], v[80:83], v[110:113], v[64:79]
	ds_read_b128 v[80:83], v175 offset:160
	s_waitcnt lgkmcnt(4)
	v_mfma_f32_32x32x16_bf16 v[64:79], v[84:87], v[118:121], v[64:79]
	ds_read_b128 v[84:87], v175 offset:192
	s_waitcnt lgkmcnt(4)
	v_mfma_f32_32x32x16_bf16 v[64:79], v[88:91], v[122:125], v[64:79]
	ds_read_b128 v[88:91], v175 offset:224
	s_waitcnt lgkmcnt(4)
	v_mfma_f32_32x32x16_bf16 v[64:79], v[92:95], v[126:129], v[64:79]
	s_waitcnt lgkmcnt(2)
	v_mfma_f32_32x32x16_bf16 v[64:79], v[80:83], v[134:137], v[64:79]
	s_waitcnt lgkmcnt(1)
	v_mfma_f32_32x32x16_bf16 v[64:79], v[84:87], v[138:141], v[64:79]
	s_waitcnt lgkmcnt(0)
	v_mfma_f32_32x32x16_bf16 v[64:79], v[88:91], v[142:145], v[64:79]
	ds_read_b128 v[80:83], v175 offset:8704
	s_waitcnt lgkmcnt(0)
	v_mfma_f32_32x32x16_bf16 v[80:95], v[80:83], v[106:109], 0
	v_mfma_f32_32x32x16_bf16 v[80:95], v[194:197], v[110:113], v[80:95]
	ds_read_b128 v[194:197], v175 offset:8768
	s_waitcnt lgkmcnt(0)
	v_mfma_f32_32x32x16_bf16 v[80:95], v[194:197], v[118:121], v[80:95]
	ds_read_b128 v[194:197], v175 offset:8800
	s_waitcnt lgkmcnt(0)
	v_mfma_f32_32x32x16_bf16 v[80:95], v[194:197], v[122:125], v[80:95]
	ds_read_b128 v[194:197], v175 offset:8832
	s_waitcnt lgkmcnt(0)
	v_mfma_f32_32x32x16_bf16 v[80:95], v[194:197], v[126:129], v[80:95]
	ds_read_b128 v[194:197], v175 offset:8864
	s_waitcnt lgkmcnt(0)
	v_mfma_f32_32x32x16_bf16 v[80:95], v[194:197], v[134:137], v[80:95]
	ds_read_b128 v[194:197], v175 offset:8896
	s_waitcnt lgkmcnt(0)
	v_mfma_f32_32x32x16_bf16 v[80:95], v[194:197], v[138:141], v[80:95]
	ds_read_b128 v[194:197], v175 offset:8928
	s_waitcnt lgkmcnt(0)
	v_mfma_f32_32x32x16_bf16 v[80:95], v[194:197], v[142:145], v[80:95]
	v_add_u32_e32 v194, s18, v161
	v_add_u32_e32 v197, 0x6f, v194
	v_cmp_lt_i32_e32 vcc, v197, v173
	s_or_b64 vcc, s[62:63], vcc
	v_add_u32_e32 v198, 0x6e, v194
	v_add_u32_e32 v195, 0x60, v194
	v_add_u32_e32 v175, 64, v194
	s_nop 4
	v_exp_f32_e32 v196, v95
	v_exp_f32_e32 v197, v94
	v_add_f32_e32 v196, 1.0, v196
	v_log_f32_e32 v196, v196
	v_add_f32_e32 v197, 1.0, v197
	v_log_f32_e32 v197, v197
	v_sub_f32_e32 v95, v95, v196
	v_exp_f32_e32 v95, v95
	v_add_f32_e32 v196, 0, v196
	v_cndmask_b32_e32 v196, 0, v196, vcc
	v_sub_f32_e32 v94, v94, v197
	v_cndmask_b32_e32 v95, 0, v95, vcc
	v_cmp_lt_i32_e32 vcc, v198, v173
	s_or_b64 vcc, s[62:63], vcc
	v_sub_f32_e32 v94, v94, v196
	v_cndmask_b32_e32 v197, 0, v197, vcc
	v_add_f32_e32 v196, v197, v196
	v_exp_f32_e32 v197, v93
	v_exp_f32_e32 v94, v94
	v_add_u32_e32 v198, 0x6d, v194
	v_add_f32_e32 v197, 1.0, v197
	v_log_f32_e32 v197, v197
	v_cndmask_b32_e32 v94, 0, v94, vcc
	v_cmp_lt_i32_e32 vcc, v198, v173
	s_or_b64 vcc, s[62:63], vcc
	v_sub_f32_e32 v93, v93, v197
	v_cndmask_b32_e32 v197, 0, v197, vcc
	v_sub_f32_e32 v93, v93, v196
	v_add_f32_e32 v196, v197, v196
	v_exp_f32_e32 v197, v92
	v_exp_f32_e32 v93, v93
	v_add_u32_e32 v198, 0x6c, v194
	v_add_f32_e32 v197, 1.0, v197
	v_log_f32_e32 v197, v197
	v_cndmask_b32_e32 v93, 0, v93, vcc
	v_cmp_lt_i32_e32 vcc, v198, v173
	s_or_b64 vcc, s[62:63], vcc
	v_sub_f32_e32 v92, v92, v197
	v_cndmask_b32_e32 v197, 0, v197, vcc
	v_sub_f32_e32 v92, v92, v196
	v_add_f32_e32 v196, v197, v196
	v_exp_f32_e32 v197, v91
	v_exp_f32_e32 v92, v92
	v_add_u32_e32 v198, 0x6b, v194
	v_add_f32_e32 v197, 1.0, v197
	v_log_f32_e32 v197, v197
	v_cndmask_b32_e32 v92, 0, v92, vcc
	v_cmp_lt_i32_e32 vcc, v198, v173
	s_or_b64 vcc, s[62:63], vcc
	v_sub_f32_e32 v91, v91, v197
	v_cndmask_b32_e32 v197, 0, v197, vcc
	v_sub_f32_e32 v91, v91, v196
	v_add_f32_e32 v196, v197, v196
	v_exp_f32_e32 v197, v90
	v_exp_f32_e32 v91, v91
	v_add_u32_e32 v198, 0x6a, v194
	v_add_f32_e32 v197, 1.0, v197
	v_log_f32_e32 v197, v197
	v_cndmask_b32_e32 v91, 0, v91, vcc
	v_cmp_lt_i32_e32 vcc, v198, v173
	s_or_b64 vcc, s[62:63], vcc
	v_sub_f32_e32 v90, v90, v197
	v_cndmask_b32_e32 v197, 0, v197, vcc
	v_sub_f32_e32 v90, v90, v196
	v_add_f32_e32 v196, v197, v196
	v_exp_f32_e32 v197, v89
	v_exp_f32_e32 v90, v90
	v_add_u32_e32 v198, 0x69, v194
	v_add_f32_e32 v197, 1.0, v197
	v_log_f32_e32 v197, v197
	v_cndmask_b32_e32 v90, 0, v90, vcc
	v_cmp_lt_i32_e32 vcc, v198, v173
	s_or_b64 vcc, s[62:63], vcc
	v_sub_f32_e32 v89, v89, v197
	v_cndmask_b32_e32 v197, 0, v197, vcc
	v_sub_f32_e32 v89, v89, v196
	v_add_f32_e32 v196, v197, v196
	v_exp_f32_e32 v197, v88
	v_exp_f32_e32 v89, v89
	v_add_u32_e32 v198, 0x68, v194
	v_add_f32_e32 v197, 1.0, v197
	v_log_f32_e32 v197, v197
	v_cndmask_b32_e32 v89, 0, v89, vcc
	v_cmp_lt_i32_e32 vcc, v198, v173
	s_or_b64 vcc, s[62:63], vcc
	v_sub_f32_e32 v88, v88, v197
	v_cndmask_b32_e32 v197, 0, v197, vcc
	v_sub_f32_e32 v88, v88, v196
	v_add_f32_e32 v196, v197, v196
	v_exp_f32_e32 v197, v87
	v_exp_f32_e32 v88, v88
	v_add_u32_e32 v198, 0x67, v194
	v_add_f32_e32 v197, 1.0, v197
	v_log_f32_e32 v197, v197
	v_cndmask_b32_e32 v88, 0, v88, vcc
	v_cmp_lt_i32_e32 vcc, v198, v173
	s_or_b64 vcc, s[62:63], vcc
	v_sub_f32_e32 v87, v87, v197
; __device__ __forceinline__ void attn_unit(int b, int h, int qb, const bf16_t* __restrict__ QK, const bf16_t* __restrict__ VT, bf16_t* __restrict__ O, const float* __restrict__ qg, const float* __restrict__ kg, ...
;     ...
;                 float run = 0.f; const int s0 = kt * 64 + kb * 32 + hi * 16;
; #pragma unroll
;                 for (int r = 15; r >= 0; --r) {
;                     const float z = p[kb][r];
;                     const float e = __builtin_amdgcn_exp2f(z);
;                     float sp = __builtin_amdgcn_logf(1.0f + e);
;                     float a = __builtin_amdgcn_exp2f(z - sp - run);
;                     if (needmask && !(s0 + r < tq)) { sp = 0.f; a = 0.f; }
;                     run += sp; p[kb][r] = a; }
	v_cndmask_b32_e32 v197, 0, v197, vcc
	v_sub_f32_e32 v87, v87, v196
	v_add_f32_e32 v196, v197, v196
	v_exp_f32_e32 v197, v86
	v_exp_f32_e32 v87, v87
	v_add_u32_e32 v198, 0x66, v194
	v_add_f32_e32 v197, 1.0, v197
	v_log_f32_e32 v197, v197
	v_cndmask_b32_e32 v87, 0, v87, vcc
	v_cmp_lt_i32_e32 vcc, v198, v173
	s_or_b64 vcc, s[62:63], vcc
	v_sub_f32_e32 v86, v86, v197
	v_cndmask_b32_e32 v197, 0, v197, vcc
	v_sub_f32_e32 v86, v86, v196
	v_add_f32_e32 v196, v197, v196
	v_exp_f32_e32 v197, v85
	v_exp_f32_e32 v86, v86
	v_add_u32_e32 v198, 0x65, v194
	v_add_f32_e32 v197, 1.0, v197
	v_log_f32_e32 v197, v197
	v_cndmask_b32_e32 v86, 0, v86, vcc
	v_cmp_lt_i32_e32 vcc, v198, v173
	s_or_b64 vcc, s[62:63], vcc
	v_sub_f32_e32 v85, v85, v197
	v_cndmask_b32_e32 v197, 0, v197, vcc
	v_sub_f32_e32 v85, v85, v196
	v_add_f32_e32 v196, v197, v196
	v_exp_f32_e32 v197, v84
	v_exp_f32_e32 v85, v85
	v_add_u32_e32 v198, 0x64, v194
	v_add_f32_e32 v197, 1.0, v197
	v_log_f32_e32 v197, v197
	v_cndmask_b32_e32 v85, 0, v85, vcc
	v_cmp_lt_i32_e32 vcc, v198, v173
	s_or_b64 vcc, s[62:63], vcc
	v_sub_f32_e32 v84, v84, v197
	v_cndmask_b32_e32 v197, 0, v197, vcc
	v_sub_f32_e32 v84, v84, v196
	v_add_f32_e32 v196, v197, v196
	v_exp_f32_e32 v197, v83
	v_exp_f32_e32 v84, v84
	v_add_u32_e32 v198, 0x63, v194
	v_add_f32_e32 v197, 1.0, v197
	v_log_f32_e32 v197, v197
	v_cndmask_b32_e32 v84, 0, v84, vcc
	v_cmp_lt_i32_e32 vcc, v198, v173
	s_or_b64 vcc, s[62:63], vcc
	v_sub_f32_e32 v83, v83, v197
	v_cndmask_b32_e32 v197, 0, v197, vcc
	v_sub_f32_e32 v83, v83, v196
	v_add_f32_e32 v196, v197, v196
	v_exp_f32_e32 v197, v82
	v_exp_f32_e32 v83, v83
	v_add_u32_e32 v198, 0x62, v194
	v_add_f32_e32 v197, 1.0, v197
	v_log_f32_e32 v197, v197
	v_cndmask_b32_e32 v83, 0, v83, vcc
	v_cmp_lt_i32_e32 vcc, v198, v173
	s_or_b64 vcc, s[62:63], vcc
	v_sub_f32_e32 v82, v82, v197
	v_cndmask_b32_e32 v197, 0, v197, vcc
	v_sub_f32_e32 v82, v82, v196
	v_add_f32_e32 v196, v197, v196
	v_exp_f32_e32 v197, v81
	v_exp_f32_e32 v82, v82
	v_add_u32_e32 v198, 0x61, v194
	v_add_f32_e32 v197, 1.0, v197
	v_log_f32_e32 v197, v197
	v_cndmask_b32_e32 v82, 0, v82, vcc
	v_cmp_lt_i32_e32 vcc, v198, v173
	s_or_b64 vcc, s[62:63], vcc
	v_sub_f32_e32 v81, v81, v197
	v_cndmask_b32_e32 v197, 0, v197, vcc
	v_sub_f32_e32 v81, v81, v196
	v_add_f32_e32 v196, v197, v196
	v_exp_f32_e32 v197, v80
	v_exp_f32_e32 v81, v81
	v_add_u32_e32 v198, 0x4e, v194
	v_add_f32_e32 v197, 1.0, v197
	v_log_f32_e32 v197, v197
	v_cndmask_b32_e32 v81, 0, v81, vcc
	v_cmp_lt_i32_e32 vcc, v195, v173
	s_or_b64 vcc, s[62:63], vcc
	v_sub_f32_e32 v80, v80, v197
	v_cndmask_b32_e32 v195, 0, v197, vcc
	v_sub_f32_e32 v80, v80, v196
	v_add_f32_e32 v195, v195, v196
	v_exp_f32_e32 v196, v79
	v_exp_f32_e32 v80, v80
	v_add_u32_e32 v197, 0x4f, v194
	v_add_f32_e32 v196, 1.0, v196
	v_log_f32_e32 v196, v196
	v_cndmask_b32_e32 v80, 0, v80, vcc
	v_cmp_lt_i32_e32 vcc, v197, v173
	v_exp_f32_e32 v197, v78
	v_sub_f32_e32 v79, v79, v196
	v_exp_f32_e32 v79, v79
	s_or_b64 vcc, s[62:63], vcc
	v_add_f32_e32 v197, 1.0, v197
	v_log_f32_e32 v197, v197
	v_add_f32_e32 v196, 0, v196
	v_cndmask_b32_e32 v79, 0, v79, vcc
	v_cndmask_b32_e32 v196, 0, v196, vcc
	v_cmp_lt_i32_e32 vcc, v198, v173
	s_or_b64 vcc, s[62:63], vcc
	v_sub_f32_e32 v78, v78, v197
	v_cndmask_b32_e32 v197, 0, v197, vcc
	v_sub_f32_e32 v78, v78, v196
	v_add_f32_e32 v196, v197, v196
	v_exp_f32_e32 v197, v77
	v_exp_f32_e32 v78, v78
	v_add_u32_e32 v198, 0x4d, v194
	v_add_f32_e32 v197, 1.0, v197
	v_log_f32_e32 v197, v197
	v_cndmask_b32_e32 v78, 0, v78, vcc
	v_cmp_lt_i32_e32 vcc, v198, v173
	s_or_b64 vcc, s[62:63], vcc
	v_sub_f32_e32 v77, v77, v197
	v_cndmask_b32_e32 v197, 0, v197, vcc
	v_sub_f32_e32 v77, v77, v196
	v_add_f32_e32 v196, v197, v196
	v_exp_f32_e32 v197, v76
	v_exp_f32_e32 v77, v77
	v_add_u32_e32 v198, 0x4c, v194
	v_add_f32_e32 v197, 1.0, v197
	v_log_f32_e32 v197, v197
	v_cndmask_b32_e32 v77, 0, v77, vcc
	v_cmp_lt_i32_e32 vcc, v198, v173
	s_or_b64 vcc, s[62:63], vcc
	v_sub_f32_e32 v76, v76, v197
	v_cndmask_b32_e32 v197, 0, v197, vcc
	v_sub_f32_e32 v76, v76, v196
	v_add_f32_e32 v196, v197, v196
	v_exp_f32_e32 v197, v75
	v_exp_f32_e32 v76, v76
	v_add_u32_e32 v198, 0x4b, v194
	v_add_f32_e32 v197, 1.0, v197
	v_log_f32_e32 v197, v197
	v_cndmask_b32_e32 v76, 0, v76, vcc
	v_cmp_lt_i32_e32 vcc, v198, v173
	s_or_b64 vcc, s[62:63], vcc
	v_sub_f32_e32 v75, v75, v197
	v_cndmask_b32_e32 v197, 0, v197, vcc
	v_sub_f32_e32 v75, v75, v196
	v_add_f32_e32 v196, v197, v196
	v_exp_f32_e32 v197, v74
	v_exp_f32_e32 v75, v75
	v_add_u32_e32 v198, 0x4a, v194
	v_add_f32_e32 v197, 1.0, v197
	v_log_f32_e32 v197, v197
	v_cndmask_b32_e32 v75, 0, v75, vcc
	v_cmp_lt_i32_e32 vcc, v198, v173
	s_or_b64 vcc, s[62:63], vcc
	v_sub_f32_e32 v74, v74, v197
	v_cndmask_b32_e32 v197, 0, v197, vcc
	v_sub_f32_e32 v74, v74, v196
	v_add_f32_e32 v196, v197, v196
	v_exp_f32_e32 v197, v73
	v_exp_f32_e32 v74, v74
	v_add_u32_e32 v198, 0x49, v194
	v_add_f32_e32 v197, 1.0, v197
	v_log_f32_e32 v197, v197
	v_cndmask_b32_e32 v74, 0, v74, vcc
	v_cmp_lt_i32_e32 vcc, v198, v173
	s_or_b64 vcc, s[62:63], vcc
	v_sub_f32_e32 v73, v73, v197
	v_cndmask_b32_e32 v197, 0, v197, vcc
	v_sub_f32_e32 v73, v73, v196
	v_add_f32_e32 v196, v197, v196
	v_exp_f32_e32 v197, v72
	v_exp_f32_e32 v73, v73
	v_add_u32_e32 v198, 0x48, v194
	v_add_f32_e32 v197, 1.0, v197
	v_log_f32_e32 v197, v197
	v_cndmask_b32_e32 v73, 0, v73, vcc
	v_cmp_lt_i32_e32 vcc, v198, v173
	s_or_b64 vcc, s[62:63], vcc
	v_sub_f32_e32 v72, v72, v197
	v_cndmask_b32_e32 v197, 0, v197, vcc
	v_sub_f32_e32 v72, v72, v196
	v_add_f32_e32 v196, v197, v196
	v_exp_f32_e32 v197, v71
	v_exp_f32_e32 v72, v72
	v_add_u32_e32 v198, 0x47, v194
	v_add_f32_e32 v197, 1.0, v197
; #define LAS __attribute__((address_space(3)))
; __device__ __forceinline__ unsigned pk2(float lo, float hi) { f32x2 v = {lo, hi}; bf16x2_t b = __builtin_convertvector(v, bf16x2_t); return __builtin_bit_cast(unsigned, b); }
; __device__ __forceinline__ void attn_unit(int b, int h, int qb, const bf16_t* __restrict__ QK, const bf16_t* __restrict__ VT, bf16_t* __restrict__ O, const float* __restrict__ qg, const float* __restrict__ kg, ...
;     ...
;                 for (int r = 15; r >= 0; --r) {
;                     const float z = p[kb][r];
;                     const float e = __builtin_amdgcn_exp2f(z);
;                     float sp = __builtin_amdgcn_logf(1.0f + e);
;                     float a = __builtin_amdgcn_exp2f(z - sp - run);
;                     if (needmask && !(s0 + r < tq)) { sp = 0.f; a = 0.f; }
;                     run += sp; p[kb][r] = a; }
;                 T[kb] = run; }
;             const float T0o = __shfl_xor(T[0], 32), T1o = __shfl_xor(T[1], 32);
;             const float base1 = R + (hi == 0 ? T1o : 0.f), base0 = R + T[1] + T1o + (hi == 0 ? T0o : 0.f);
;             const float f0 = __builtin_amdgcn_exp2f(-base0), f1 = __builtin_amdgcn_exp2f(-base1);
;             R += (T[0] + T0o) + (T[1] + T1o);
;             bf16x8 pa[2][2];
; #pragma unroll
;             for (int kb = 0; kb < 2; ++kb) { const float f = kb ? f1 : f0;
; #pragma unroll
;                 for (int s2 = 0; s2 < 2; ++s2) { u32x4 w;
;                     w.x = pk2(p[kb][8 * s2 + 0] * f, p[kb][8 * s2 + 1] * f); w.y = pk2(p[kb][8 * s2 + 2] * f, p[kb][8 * s2 + 3] * f);
;                     w.z = pk2(p[kb][8 * s2 + 4] * f, p[kb][8 * s2 + 5] * f); w.w = pk2(p[kb][8 * s2 + 6] * f, p[kb][8 * s2 + 7] * f);
;                     pa[kb][s2] = __builtin_bit_cast(bf16x8, w); } }
; #pragma unroll
;             for (int d = 0; d < 4; ++d)
; #pragma unroll
;                 for (int kb = 0; kb < 2; ++kb)
; #pragma unroll
;                     for (int s2 = 0; s2 < 2; ++s2) { const bf16x8 vb = *(const LAS bf16x8*)(vb_ + d * 32 * AV_ROWB + kb * 64 + s2 * 16); o[d] = __builtin_amdgcn_mfma_f32_32x32x16_bf16(pa[kb][s2], vb, o[d], 0, 0, 0); }
;             wdone = __all(R >= ATT_DONE_LOG2) != 0;
	v_log_f32_e32 v197, v197
	v_cndmask_b32_e32 v72, 0, v72, vcc
	v_cmp_lt_i32_e32 vcc, v198, v173
	s_or_b64 vcc, s[62:63], vcc
	v_sub_f32_e32 v71, v71, v197
	v_cndmask_b32_e32 v197, 0, v197, vcc
	v_sub_f32_e32 v71, v71, v196
	v_add_f32_e32 v196, v197, v196
	v_exp_f32_e32 v197, v70
	v_exp_f32_e32 v71, v71
	v_add_u32_e32 v198, 0x46, v194
	v_add_f32_e32 v197, 1.0, v197
	v_log_f32_e32 v197, v197
	v_cndmask_b32_e32 v71, 0, v71, vcc
	v_cmp_lt_i32_e32 vcc, v198, v173
	s_or_b64 vcc, s[62:63], vcc
	v_sub_f32_e32 v70, v70, v197
	v_cndmask_b32_e32 v197, 0, v197, vcc
	v_sub_f32_e32 v70, v70, v196
	v_add_f32_e32 v196, v197, v196
	v_exp_f32_e32 v197, v69
	v_exp_f32_e32 v70, v70
	v_add_u32_e32 v198, 0x45, v194
	v_add_f32_e32 v197, 1.0, v197
	v_log_f32_e32 v197, v197
	v_cndmask_b32_e32 v70, 0, v70, vcc
	v_cmp_lt_i32_e32 vcc, v198, v173
	s_or_b64 vcc, s[62:63], vcc
	v_sub_f32_e32 v69, v69, v197
	v_cndmask_b32_e32 v197, 0, v197, vcc
	v_sub_f32_e32 v69, v69, v196
	v_add_f32_e32 v196, v197, v196
	v_exp_f32_e32 v197, v68
	v_exp_f32_e32 v69, v69
	v_add_u32_e32 v198, 0x44, v194
	v_add_f32_e32 v197, 1.0, v197
	v_log_f32_e32 v197, v197
	v_cndmask_b32_e32 v69, 0, v69, vcc
	v_cmp_lt_i32_e32 vcc, v198, v173
	s_or_b64 vcc, s[62:63], vcc
	v_sub_f32_e32 v68, v68, v197
	v_cndmask_b32_e32 v197, 0, v197, vcc
	v_sub_f32_e32 v68, v68, v196
	v_add_f32_e32 v196, v197, v196
	v_exp_f32_e32 v197, v67
	v_exp_f32_e32 v68, v68
	v_add_u32_e32 v198, 0x43, v194
	v_add_f32_e32 v197, 1.0, v197
	v_log_f32_e32 v197, v197
	v_cndmask_b32_e32 v68, 0, v68, vcc
	v_cmp_lt_i32_e32 vcc, v198, v173
	s_or_b64 vcc, s[62:63], vcc
	v_sub_f32_e32 v67, v67, v197
	v_cndmask_b32_e32 v197, 0, v197, vcc
	v_sub_f32_e32 v67, v67, v196
	v_add_f32_e32 v196, v197, v196
	v_exp_f32_e32 v197, v66
	v_exp_f32_e32 v67, v67
	v_add_u32_e32 v198, 0x42, v194
	v_add_u32_e32 v194, 0x41, v194
	v_add_f32_e32 v197, 1.0, v197
	v_log_f32_e32 v197, v197
	v_cndmask_b32_e32 v67, 0, v67, vcc
	v_cmp_lt_i32_e32 vcc, v198, v173
	s_or_b64 vcc, s[62:63], vcc
	v_sub_f32_e32 v66, v66, v197
	v_cndmask_b32_e32 v197, 0, v197, vcc
	v_sub_f32_e32 v66, v66, v196
	v_add_f32_e32 v196, v197, v196
	v_exp_f32_e32 v197, v65
	v_exp_f32_e32 v66, v66
	v_add_f32_e32 v198, v169, v195
	v_add_f32_e32 v197, 1.0, v197
	v_log_f32_e32 v197, v197
	v_cndmask_b32_e32 v66, 0, v66, vcc
	v_cmp_lt_i32_e32 vcc, v194, v173
	s_or_b64 vcc, s[62:63], vcc
	v_sub_f32_e32 v65, v65, v197
	v_cndmask_b32_e32 v194, 0, v197, vcc
	v_sub_f32_e32 v65, v65, v196
	v_add_f32_e32 v194, v194, v196
	v_exp_f32_e32 v196, v64
	v_exp_f32_e32 v65, v65
	v_add_f32_e32 v196, 1.0, v196
	v_log_f32_e32 v196, v196
	v_cndmask_b32_e32 v65, 0, v65, vcc
	v_cmp_lt_i32_e32 vcc, v175, v173
	s_or_b64 vcc, s[62:63], vcc
	v_sub_f32_e32 v64, v64, v196
	v_cndmask_b32_e32 v175, 0, v196, vcc
	v_add_f32_e32 v175, v175, v194
	v_sub_f32_e32 v64, v64, v194
	ds_bpermute_b32 v194, v157, v175
	ds_bpermute_b32 v196, v157, v195
	v_exp_f32_e32 v64, v64
	s_waitcnt lgkmcnt(1)
	v_cndmask_b32_e64 v199, 0, v194, s[4:5]
	s_waitcnt lgkmcnt(0)
	v_add_f32_e32 v198, v198, v196
	v_add_f32_e32 v198, v199, v198
	v_exp_f32_e64 v198, -v198
	v_cndmask_b32_e32 v64, 0, v64, vcc
	v_cndmask_b32_e64 v197, 0, v196, s[4:5]
	v_add_f32_e32 v197, v169, v197
	v_mul_f32_e32 v64, v64, v198
	v_mul_f32_e32 v65, v65, v198
	v_cvt_pk_bf16_f32 v64, v64, v65
	v_mul_f32_e32 v65, v66, v198
	v_mul_f32_e32 v66, v67, v198
	v_cvt_pk_bf16_f32 v65, v65, v66
	v_mul_f32_e32 v66, v68, v198
	v_mul_f32_e32 v67, v69, v198
	v_cvt_pk_bf16_f32 v66, v66, v67
	v_mul_f32_e32 v67, v70, v198
	v_mul_f32_e32 v68, v71, v198
	v_exp_f32_e64 v197, -v197
	v_cvt_pk_bf16_f32 v67, v67, v68
	v_mul_f32_e32 v68, v72, v198
	v_mul_f32_e32 v69, v73, v198
	v_cvt_pk_bf16_f32 v68, v68, v69
	v_mul_f32_e32 v69, v74, v198
	v_mul_f32_e32 v70, v75, v198
	v_cvt_pk_bf16_f32 v69, v69, v70
	v_mul_f32_e32 v70, v76, v198
	v_mul_f32_e32 v71, v77, v198
	v_cvt_pk_bf16_f32 v70, v70, v71
	v_mul_f32_e32 v71, v78, v198
	v_mul_f32_e32 v72, v79, v198
	v_cvt_pk_bf16_f32 v71, v71, v72
	v_mul_f32_e32 v72, v197, v80
	v_mul_f32_e32 v73, v197, v81
	v_cvt_pk_bf16_f32 v76, v72, v73
	v_mul_f32_e32 v72, v197, v82
	v_mul_f32_e32 v73, v197, v83
	v_cvt_pk_bf16_f32 v77, v72, v73
	v_mul_f32_e32 v72, v197, v84
	v_mul_f32_e32 v73, v197, v85
	v_cvt_pk_bf16_f32 v78, v72, v73
	v_mul_f32_e32 v72, v197, v86
	v_mul_f32_e32 v73, v197, v87
	v_cvt_pk_bf16_f32 v79, v72, v73
	v_mul_f32_e32 v72, v197, v88
	v_mul_f32_e32 v73, v197, v89
	v_cvt_pk_bf16_f32 v72, v72, v73
	v_mul_f32_e32 v73, v197, v90
	v_mul_f32_e32 v74, v197, v91
	v_cvt_pk_bf16_f32 v73, v73, v74
	v_mul_f32_e32 v74, v197, v92
	v_mul_f32_e32 v75, v197, v93
	v_cvt_pk_bf16_f32 v74, v74, v75
	v_mul_f32_e32 v75, v197, v94
	v_mul_f32_e32 v80, v197, v95
	v_add_u32_e32 v88, s16, v191
	v_cvt_pk_bf16_f32 v75, v75, v80
	ds_read_b128 v[80:83], v88 offset:34816
	ds_read_b128 v[84:87], v88 offset:34832
	ds_read_b128 v[92:95], v88 offset:34880
	s_waitcnt lgkmcnt(2)
	v_mfma_f32_32x32x16_bf16 v[0:15], v[64:67], v[80:83], v[0:15]
	ds_read_b128 v[80:83], v88 offset:34896
	v_add_f32_e32 v175, v175, v194
	v_add_f32_e32 v194, v195, v196
	v_add_f32_e32 v175, v175, v194
	v_add_f32_e32 v169, v169, v175
	v_cmp_le_f32_e32 vcc, s72, v169
	s_cmp_eq_u64 vcc, exec
	s_waitcnt lgkmcnt(2)
	v_mfma_f32_32x32x16_bf16 v[0:15], v[68:71], v[84:87], v[0:15]
	ds_read_b128 v[84:87], v88 offset:39424
	s_cselect_b64 s[16:17], -1, 0
	s_waitcnt lgkmcnt(2)
	v_mfma_f32_32x32x16_bf16 v[0:15], v[76:79], v[92:95], v[0:15]
	ds_read_b128 v[92:95], v88 offset:39440
	s_waitcnt lgkmcnt(2)
	v_mfma_f32_32x32x16_bf16 v[0:15], v[72:75], v[80:83], v[0:15]
	ds_read_b128 v[80:83], v88 offset:39488
	s_waitcnt lgkmcnt(2)
	v_mfma_f32_32x32x16_bf16 v[48:63], v[64:67], v[84:87], v[48:63]
	ds_read_b128 v[84:87], v88 offset:39504
	s_waitcnt lgkmcnt(2)
	v_mfma_f32_32x32x16_bf16 v[48:63], v[68:71], v[92:95], v[48:63]
	ds_read_b128 v[92:95], v88 offset:44032
	s_waitcnt lgkmcnt(2)
	v_mfma_f32_32x32x16_bf16 v[48:63], v[76:79], v[80:83], v[48:63]
	ds_read_b128 v[80:83], v88 offset:44048
	s_waitcnt lgkmcnt(2)
	v_mfma_f32_32x32x16_bf16 v[48:63], v[72:75], v[84:87], v[48:63]
	ds_read_b128 v[84:87], v88 offset:44096
	s_waitcnt lgkmcnt(2)
	v_mfma_f32_32x32x16_bf16 v[32:47], v[64:67], v[92:95], v[32:47]
	ds_read_b128 v[92:95], v88 offset:44112
	s_waitcnt lgkmcnt(2)
	v_mfma_f32_32x32x16_bf16 v[32:47], v[68:71], v[80:83], v[32:47]
	ds_read_b128 v[80:83], v88 offset:48640
	s_waitcnt lgkmcnt(2)
	v_mfma_f32_32x32x16_bf16 v[32:47], v[76:79], v[84:87], v[32:47]
	ds_read_b128 v[84:87], v88 offset:48656
	s_waitcnt lgkmcnt(2)
	v_mfma_f32_32x32x16_bf16 v[32:47], v[72:75], v[92:95], v[32:47]
	ds_read_b128 v[92:95], v88 offset:48704
	s_waitcnt lgkmcnt(2)
	v_mfma_f32_32x32x16_bf16 v[16:31], v[64:67], v[80:83], v[16:31]
	ds_read_b128 v[80:83], v88 offset:48720
	s_waitcnt lgkmcnt(2)
	v_mfma_f32_32x32x16_bf16 v[16:31], v[68:71], v[84:87], v[16:31]
	s_waitcnt lgkmcnt(1)
	v_mfma_f32_32x32x16_bf16 v[16:31], v[76:79], v[92:95], v[16:31]
	s_waitcnt lgkmcnt(0)
	v_mfma_f32_32x32x16_bf16 v[16:31], v[72:75], v[80:83], v[16:31]

; #define LAS __attribute__((address_space(3)))
; __device__ __forceinline__ void attn_unit(int b, int h, int qb, const bf16_t* __restrict__ QK, const bf16_t* __restrict__ VT, bf16_t* __restrict__ O, const float* __restrict__ qg, const float* __restrict__ kg, ...
;     ...
;             const LAS unsigned char* kb_ = Kb + buf * AK_BUF + kfo; const LAS unsigned char* vb_ = Vb + buf * AV_BUF + vfo;
;             f32x16 p[2];
; #pragma unroll
;             for (int kb = 0; kb < 2; ++kb) {
; #pragma unroll
;                 for (int r = 0; r < 16; ++r) p[kb][r] = 0.f;
; #pragma unroll
;                 for (int ks = 0; ks < 8; ++ks) { const bf16x8 a = *(const LAS bf16x8*)(kb_ + kb * 32 * AK_ROWB + ks * 32); p[kb] = __builtin_amdgcn_mfma_f32_32x32x16_bf16(a, qr[ks], p[kb], 0, 0, 0); }
;             }
;             const bool needmask = (kt * 64 + 63 >= q0 + wid * 32);
;             float T[2];
; #pragma unroll
;     ...
;                 float run = 0.f; const int s0 = kt * 64 + kb * 32 + hi * 16;
; #pragma unroll
;                 for (int r = 15; r >= 0; --r) {
;                     const float z = p[kb][r];
;                     const float e = __builtin_amdgcn_exp2f(z);
;                     float sp = __builtin_amdgcn_logf(1.0f + e);
;                     float a = __builtin_amdgcn_exp2f(z - sp - run);
;                     if (needmask && !(s0 + r < tq)) { sp = 0.f; a = 0.f; }
;                     run += sp; p[kb][r] = a; }
.LBB0_481:
	s_xor_b64 s[16:17], s[16:17], -1
	s_andn2_b64 vcc, exec, s[16:17]
	s_mov_b64 s[16:17], -1
	s_cbranch_vccnz .LBB0_484
	s_add_i32 s3, s18, 64
	s_cmp_ge_i32 s3, s2
	s_mov_b64 s[16:17], 0
	s_cbranch_scc1 .LBB0_484
	s_mul_i32 s3, s24, 0x4400
	v_add_u32_e32 v171, s3, v190
	ds_read_b128 v[64:67], v171
	ds_read_b128 v[80:83], v171 offset:32
	ds_read_b128 v[84:87], v171 offset:64
	ds_read_b128 v[88:91], v171 offset:96
	ds_read_b128 v[92:95], v171 offset:128
	v_add_u32_e32 v175, s18, v161
	s_add_i32 s3, s18, 0x7f
	s_cmp_lt_i32 s3, s23
	s_waitcnt lgkmcnt(4)
	v_mfma_f32_32x32x16_bf16 v[64:79], v[64:67], v[106:109], 0
	s_cselect_b64 s[62:63], -1, 0
	v_add_u32_e32 v184, 0x60, v175
	s_mul_i32 s16, s24, 0x4800
	ds_read_b128 v[192:195], v171 offset:8736
	s_waitcnt lgkmcnt(4)
	v_mfma_f32_32x32x16_bf16 v[64:79], v[80:83], v[110:113], v[64:79]
	ds_read_b128 v[80:83], v171 offset:160
	s_waitcnt lgkmcnt(4)
	v_mfma_f32_32x32x16_bf16 v[64:79], v[84:87], v[118:121], v[64:79]
	ds_read_b128 v[84:87], v171 offset:192
	s_waitcnt lgkmcnt(4)
	v_mfma_f32_32x32x16_bf16 v[64:79], v[88:91], v[122:125], v[64:79]
	ds_read_b128 v[88:91], v171 offset:224
	s_waitcnt lgkmcnt(4)
	v_mfma_f32_32x32x16_bf16 v[64:79], v[92:95], v[126:129], v[64:79]
	s_waitcnt lgkmcnt(2)
	v_mfma_f32_32x32x16_bf16 v[64:79], v[80:83], v[134:137], v[64:79]
	s_waitcnt lgkmcnt(1)
	v_mfma_f32_32x32x16_bf16 v[64:79], v[84:87], v[138:141], v[64:79]
	s_waitcnt lgkmcnt(0)
	v_mfma_f32_32x32x16_bf16 v[64:79], v[88:91], v[142:145], v[64:79]
	ds_read_b128 v[80:83], v171 offset:8704
	s_waitcnt lgkmcnt(0)
	v_mfma_f32_32x32x16_bf16 v[80:95], v[80:83], v[106:109], 0
	v_mfma_f32_32x32x16_bf16 v[80:95], v[192:195], v[110:113], v[80:95]
	ds_read_b128 v[192:195], v171 offset:8768
	s_waitcnt lgkmcnt(0)
	v_mfma_f32_32x32x16_bf16 v[80:95], v[192:195], v[118:121], v[80:95]
	ds_read_b128 v[192:195], v171 offset:8800
	s_waitcnt lgkmcnt(0)
	v_mfma_f32_32x32x16_bf16 v[80:95], v[192:195], v[122:125], v[80:95]
	ds_read_b128 v[192:195], v171 offset:8832
	s_waitcnt lgkmcnt(0)
	v_mfma_f32_32x32x16_bf16 v[80:95], v[192:195], v[126:129], v[80:95]
	ds_read_b128 v[192:195], v171 offset:8864
	s_waitcnt lgkmcnt(0)
	v_mfma_f32_32x32x16_bf16 v[80:95], v[192:195], v[134:137], v[80:95]
	ds_read_b128 v[192:195], v171 offset:8896
	s_waitcnt lgkmcnt(0)
	v_mfma_f32_32x32x16_bf16 v[80:95], v[192:195], v[138:141], v[80:95]
	ds_read_b128 v[192:195], v171 offset:8928
	v_add_u32_e32 v171, 64, v175
	s_waitcnt lgkmcnt(0)
	v_mfma_f32_32x32x16_bf16 v[80:95], v[192:195], v[142:145], v[80:95]
	v_add_u32_e32 v193, 0x6f, v175
	v_cmp_lt_i32_e32 vcc, v193, v173
	s_or_b64 vcc, s[62:63], vcc
	v_add_u32_e32 v194, 0x6e, v175
	s_nop 7
	v_exp_f32_e32 v192, v95
	v_exp_f32_e32 v193, v94
	v_add_f32_e32 v192, 1.0, v192
	v_log_f32_e32 v192, v192
	v_add_f32_e32 v193, 1.0, v193
	v_log_f32_e32 v193, v193
	v_sub_f32_e32 v95, v95, v192
	v_exp_f32_e32 v95, v95
	v_add_f32_e32 v192, 0, v192
	v_cndmask_b32_e32 v192, 0, v192, vcc
	v_sub_f32_e32 v94, v94, v193
	v_cndmask_b32_e32 v95, 0, v95, vcc
	v_cmp_lt_i32_e32 vcc, v194, v173
	s_or_b64 vcc, s[62:63], vcc
	v_sub_f32_e32 v94, v94, v192
	v_cndmask_b32_e32 v193, 0, v193, vcc
	v_add_f32_e32 v192, v193, v192
	v_exp_f32_e32 v193, v93
	v_exp_f32_e32 v94, v94
	v_add_u32_e32 v194, 0x6d, v175
	v_add_f32_e32 v193, 1.0, v193
	v_log_f32_e32 v193, v193
	v_cndmask_b32_e32 v94, 0, v94, vcc
	v_cmp_lt_i32_e32 vcc, v194, v173
	s_or_b64 vcc, s[62:63], vcc
	v_sub_f32_e32 v93, v93, v193
	v_cndmask_b32_e32 v193, 0, v193, vcc
	v_sub_f32_e32 v93, v93, v192
	v_add_f32_e32 v192, v193, v192
	v_exp_f32_e32 v193, v92
	v_exp_f32_e32 v93, v93
	v_add_u32_e32 v194, 0x6c, v175
	v_add_f32_e32 v193, 1.0, v193
	v_log_f32_e32 v193, v193
	v_cndmask_b32_e32 v93, 0, v93, vcc
	v_cmp_lt_i32_e32 vcc, v194, v173
	s_or_b64 vcc, s[62:63], vcc
	v_sub_f32_e32 v92, v92, v193
	v_cndmask_b32_e32 v193, 0, v193, vcc
	v_sub_f32_e32 v92, v92, v192
	v_add_f32_e32 v192, v193, v192
	v_exp_f32_e32 v193, v91
	v_exp_f32_e32 v92, v92
	v_add_u32_e32 v194, 0x6b, v175
	v_add_f32_e32 v193, 1.0, v193
	v_log_f32_e32 v193, v193
	v_cndmask_b32_e32 v92, 0, v92, vcc
	v_cmp_lt_i32_e32 vcc, v194, v173
	s_or_b64 vcc, s[62:63], vcc
	v_sub_f32_e32 v91, v91, v193
	v_cndmask_b32_e32 v193, 0, v193, vcc
	v_sub_f32_e32 v91, v91, v192
	v_add_f32_e32 v192, v193, v192
	v_exp_f32_e32 v193, v90
	v_exp_f32_e32 v91, v91
	v_add_u32_e32 v194, 0x6a, v175
	v_add_f32_e32 v193, 1.0, v193
	v_log_f32_e32 v193, v193
	v_cndmask_b32_e32 v91, 0, v91, vcc
	v_cmp_lt_i32_e32 vcc, v194, v173
	s_or_b64 vcc, s[62:63], vcc
	v_sub_f32_e32 v90, v90, v193
	v_cndmask_b32_e32 v193, 0, v193, vcc
	v_sub_f32_e32 v90, v90, v192
	v_add_f32_e32 v192, v193, v192
	v_exp_f32_e32 v193, v89
	v_exp_f32_e32 v90, v90
	v_add_u32_e32 v194, 0x69, v175
	v_add_f32_e32 v193, 1.0, v193
	v_log_f32_e32 v193, v193
	v_cndmask_b32_e32 v90, 0, v90, vcc
	v_cmp_lt_i32_e32 vcc, v194, v173
	s_or_b64 vcc, s[62:63], vcc
	v_sub_f32_e32 v89, v89, v193
	v_cndmask_b32_e32 v193, 0, v193, vcc
	v_sub_f32_e32 v89, v89, v192
	v_add_f32_e32 v192, v193, v192
	v_exp_f32_e32 v193, v88
	v_exp_f32_e32 v89, v89
	v_add_u32_e32 v194, 0x68, v175
	v_add_f32_e32 v193, 1.0, v193
	v_log_f32_e32 v193, v193
	v_cndmask_b32_e32 v89, 0, v89, vcc
	v_cmp_lt_i32_e32 vcc, v194, v173
	s_or_b64 vcc, s[62:63], vcc
	v_sub_f32_e32 v88, v88, v193
	v_cndmask_b32_e32 v193, 0, v193, vcc
	v_sub_f32_e32 v88, v88, v192
	v_add_f32_e32 v192, v193, v192
	v_exp_f32_e32 v193, v87
	v_exp_f32_e32 v88, v88
	v_add_u32_e32 v194, 0x67, v175
	v_add_f32_e32 v193, 1.0, v193
	v_log_f32_e32 v193, v193
	v_cndmask_b32_e32 v88, 0, v88, vcc
	v_cmp_lt_i32_e32 vcc, v194, v173
	s_or_b64 vcc, s[62:63], vcc
	v_sub_f32_e32 v87, v87, v193
; __device__ __forceinline__ void attn_unit(int b, int h, int qb, const bf16_t* __restrict__ QK, const bf16_t* __restrict__ VT, bf16_t* __restrict__ O, const float* __restrict__ qg, const float* __restrict__ kg, ...
;     ...
;                 float run = 0.f; const int s0 = kt * 64 + kb * 32 + hi * 16;
; #pragma unroll
;                 for (int r = 15; r >= 0; --r) {
;                     const float z = p[kb][r];
;                     const float e = __builtin_amdgcn_exp2f(z);
;                     float sp = __builtin_amdgcn_logf(1.0f + e);
;                     float a = __builtin_amdgcn_exp2f(z - sp - run);
;                     if (needmask && !(s0 + r < tq)) { sp = 0.f; a = 0.f; }
;                     run += sp; p[kb][r] = a; }
	v_cndmask_b32_e32 v193, 0, v193, vcc
	v_sub_f32_e32 v87, v87, v192
	v_add_f32_e32 v192, v193, v192
	v_exp_f32_e32 v193, v86
	v_exp_f32_e32 v87, v87
	v_add_u32_e32 v194, 0x66, v175
	v_add_f32_e32 v193, 1.0, v193
	v_log_f32_e32 v193, v193
	v_cndmask_b32_e32 v87, 0, v87, vcc
	v_cmp_lt_i32_e32 vcc, v194, v173
	s_or_b64 vcc, s[62:63], vcc
	v_sub_f32_e32 v86, v86, v193
	v_cndmask_b32_e32 v193, 0, v193, vcc
	v_sub_f32_e32 v86, v86, v192
	v_add_f32_e32 v192, v193, v192
	v_exp_f32_e32 v193, v85
	v_exp_f32_e32 v86, v86
	v_add_u32_e32 v194, 0x65, v175
	v_add_f32_e32 v193, 1.0, v193
	v_log_f32_e32 v193, v193
	v_cndmask_b32_e32 v86, 0, v86, vcc
	v_cmp_lt_i32_e32 vcc, v194, v173
	s_or_b64 vcc, s[62:63], vcc
	v_sub_f32_e32 v85, v85, v193
	v_cndmask_b32_e32 v193, 0, v193, vcc
	v_sub_f32_e32 v85, v85, v192
	v_add_f32_e32 v192, v193, v192
	v_exp_f32_e32 v193, v84
	v_exp_f32_e32 v85, v85
	v_add_u32_e32 v194, 0x64, v175
	v_add_f32_e32 v193, 1.0, v193
	v_log_f32_e32 v193, v193
	v_cndmask_b32_e32 v85, 0, v85, vcc
	v_cmp_lt_i32_e32 vcc, v194, v173
	s_or_b64 vcc, s[62:63], vcc
	v_sub_f32_e32 v84, v84, v193
	v_cndmask_b32_e32 v193, 0, v193, vcc
	v_sub_f32_e32 v84, v84, v192
	v_add_f32_e32 v192, v193, v192
	v_exp_f32_e32 v193, v83
	v_exp_f32_e32 v84, v84
	v_add_u32_e32 v194, 0x63, v175
	v_add_f32_e32 v193, 1.0, v193
	v_log_f32_e32 v193, v193
	v_cndmask_b32_e32 v84, 0, v84, vcc
	v_cmp_lt_i32_e32 vcc, v194, v173
	s_or_b64 vcc, s[62:63], vcc
	v_sub_f32_e32 v83, v83, v193
	v_cndmask_b32_e32 v193, 0, v193, vcc
	v_sub_f32_e32 v83, v83, v192
	v_add_f32_e32 v192, v193, v192
	v_exp_f32_e32 v193, v82
	v_exp_f32_e32 v83, v83
	v_add_u32_e32 v194, 0x62, v175
	v_add_f32_e32 v193, 1.0, v193
	v_log_f32_e32 v193, v193
	v_cndmask_b32_e32 v83, 0, v83, vcc
	v_cmp_lt_i32_e32 vcc, v194, v173
	s_or_b64 vcc, s[62:63], vcc
	v_sub_f32_e32 v82, v82, v193
	v_cndmask_b32_e32 v193, 0, v193, vcc
	v_sub_f32_e32 v82, v82, v192
	v_add_f32_e32 v192, v193, v192
	v_exp_f32_e32 v193, v81
	v_exp_f32_e32 v82, v82
	v_add_u32_e32 v194, 0x61, v175
	v_add_f32_e32 v193, 1.0, v193
	v_log_f32_e32 v193, v193
	v_cndmask_b32_e32 v82, 0, v82, vcc
	v_cmp_lt_i32_e32 vcc, v194, v173
	s_or_b64 vcc, s[62:63], vcc
	v_sub_f32_e32 v81, v81, v193
	v_cndmask_b32_e32 v193, 0, v193, vcc
	v_sub_f32_e32 v81, v81, v192
	v_add_f32_e32 v192, v193, v192
	v_exp_f32_e32 v193, v80
	v_exp_f32_e32 v81, v81
	v_add_u32_e32 v194, 0x4e, v175
	v_add_f32_e32 v193, 1.0, v193
	v_log_f32_e32 v193, v193
	v_cndmask_b32_e32 v81, 0, v81, vcc
	v_cmp_lt_i32_e32 vcc, v184, v173
	s_or_b64 vcc, s[62:63], vcc
	v_sub_f32_e32 v80, v80, v193
	v_cndmask_b32_e32 v184, 0, v193, vcc
	v_sub_f32_e32 v80, v80, v192
	v_add_f32_e32 v184, v184, v192
	v_exp_f32_e32 v192, v79
	v_exp_f32_e32 v80, v80
	v_add_u32_e32 v193, 0x4f, v175
	v_add_f32_e32 v192, 1.0, v192
	v_log_f32_e32 v192, v192
	v_cndmask_b32_e32 v80, 0, v80, vcc
	v_cmp_lt_i32_e32 vcc, v193, v173
	v_exp_f32_e32 v193, v78
	v_sub_f32_e32 v79, v79, v192
	v_exp_f32_e32 v79, v79
	s_or_b64 vcc, s[62:63], vcc
	v_add_f32_e32 v193, 1.0, v193
	v_log_f32_e32 v193, v193
	v_add_f32_e32 v192, 0, v192
	v_cndmask_b32_e32 v79, 0, v79, vcc
	v_cndmask_b32_e32 v192, 0, v192, vcc
	v_cmp_lt_i32_e32 vcc, v194, v173
	s_or_b64 vcc, s[62:63], vcc
	v_sub_f32_e32 v78, v78, v193
	v_cndmask_b32_e32 v193, 0, v193, vcc
	v_sub_f32_e32 v78, v78, v192
	v_add_f32_e32 v192, v193, v192
	v_exp_f32_e32 v193, v77
	v_exp_f32_e32 v78, v78
	v_add_u32_e32 v194, 0x4d, v175
	v_add_f32_e32 v193, 1.0, v193
	v_log_f32_e32 v193, v193
	v_cndmask_b32_e32 v78, 0, v78, vcc
	v_cmp_lt_i32_e32 vcc, v194, v173
	s_or_b64 vcc, s[62:63], vcc
	v_sub_f32_e32 v77, v77, v193
	v_cndmask_b32_e32 v193, 0, v193, vcc
	v_sub_f32_e32 v77, v77, v192
	v_add_f32_e32 v192, v193, v192
	v_exp_f32_e32 v193, v76
	v_exp_f32_e32 v77, v77
	v_add_u32_e32 v194, 0x4c, v175
	v_add_f32_e32 v193, 1.0, v193
	v_log_f32_e32 v193, v193
	v_cndmask_b32_e32 v77, 0, v77, vcc
	v_cmp_lt_i32_e32 vcc, v194, v173
	s_or_b64 vcc, s[62:63], vcc
	v_sub_f32_e32 v76, v76, v193
	v_cndmask_b32_e32 v193, 0, v193, vcc
	v_sub_f32_e32 v76, v76, v192
	v_add_f32_e32 v192, v193, v192
	v_exp_f32_e32 v193, v75
	v_exp_f32_e32 v76, v76
	v_add_u32_e32 v194, 0x4b, v175
	v_add_f32_e32 v193, 1.0, v193
	v_log_f32_e32 v193, v193
	v_cndmask_b32_e32 v76, 0, v76, vcc
	v_cmp_lt_i32_e32 vcc, v194, v173
	s_or_b64 vcc, s[62:63], vcc
	v_sub_f32_e32 v75, v75, v193
	v_cndmask_b32_e32 v193, 0, v193, vcc
	v_sub_f32_e32 v75, v75, v192
	v_add_f32_e32 v192, v193, v192
	v_exp_f32_e32 v193, v74
	v_exp_f32_e32 v75, v75
	v_add_u32_e32 v194, 0x4a, v175
	v_add_f32_e32 v193, 1.0, v193
	v_log_f32_e32 v193, v193
	v_cndmask_b32_e32 v75, 0, v75, vcc
	v_cmp_lt_i32_e32 vcc, v194, v173
	s_or_b64 vcc, s[62:63], vcc
	v_sub_f32_e32 v74, v74, v193
	v_cndmask_b32_e32 v193, 0, v193, vcc
	v_sub_f32_e32 v74, v74, v192
	v_add_f32_e32 v192, v193, v192
	v_exp_f32_e32 v193, v73
	v_exp_f32_e32 v74, v74
	v_add_u32_e32 v194, 0x49, v175
	v_add_f32_e32 v193, 1.0, v193
	v_log_f32_e32 v193, v193
	v_cndmask_b32_e32 v74, 0, v74, vcc
	v_cmp_lt_i32_e32 vcc, v194, v173
	s_or_b64 vcc, s[62:63], vcc
	v_sub_f32_e32 v73, v73, v193
	v_cndmask_b32_e32 v193, 0, v193, vcc
	v_sub_f32_e32 v73, v73, v192
	v_add_f32_e32 v192, v193, v192
	v_exp_f32_e32 v193, v72
	v_exp_f32_e32 v73, v73
	v_add_u32_e32 v194, 0x48, v175
	v_add_f32_e32 v193, 1.0, v193
	v_log_f32_e32 v193, v193
	v_cndmask_b32_e32 v73, 0, v73, vcc
	v_cmp_lt_i32_e32 vcc, v194, v173
	s_or_b64 vcc, s[62:63], vcc
	v_sub_f32_e32 v72, v72, v193
	v_cndmask_b32_e32 v193, 0, v193, vcc
	v_sub_f32_e32 v72, v72, v192
	v_add_f32_e32 v192, v193, v192
	v_exp_f32_e32 v193, v71
	v_exp_f32_e32 v72, v72
	v_add_u32_e32 v194, 0x47, v175
	v_add_f32_e32 v193, 1.0, v193
; #define LAS __attribute__((address_space(3)))
; __device__ __forceinline__ unsigned pk2(float lo, float hi) { f32x2 v = {lo, hi}; bf16x2_t b = __builtin_convertvector(v, bf16x2_t); return __builtin_bit_cast(unsigned, b); }
; __device__ __forceinline__ void attn_unit(int b, int h, int qb, const bf16_t* __restrict__ QK, const bf16_t* __restrict__ VT, bf16_t* __restrict__ O, const float* __restrict__ qg, const float* __restrict__ kg, ...
;     ...
;                 for (int r = 15; r >= 0; --r) {
;                     const float z = p[kb][r];
;                     const float e = __builtin_amdgcn_exp2f(z);
;                     float sp = __builtin_amdgcn_logf(1.0f + e);
;                     float a = __builtin_amdgcn_exp2f(z - sp - run);
;                     if (needmask && !(s0 + r < tq)) { sp = 0.f; a = 0.f; }
;                     run += sp; p[kb][r] = a; }
;                 T[kb] = run; }
;             const float T0o = __shfl_xor(T[0], 32), T1o = __shfl_xor(T[1], 32);
;             const float base1 = R + (hi == 0 ? T1o : 0.f), base0 = R + T[1] + T1o + (hi == 0 ? T0o : 0.f);
;             const float f0 = __builtin_amdgcn_exp2f(-base0), f1 = __builtin_amdgcn_exp2f(-base1);
;             R += (T[0] + T0o) + (T[1] + T1o);
;             bf16x8 pa[2][2];
; #pragma unroll
;             for (int kb = 0; kb < 2; ++kb) { const float f = kb ? f1 : f0;
; #pragma unroll
;                 for (int s2 = 0; s2 < 2; ++s2) { u32x4 w;
;                     w.x = pk2(p[kb][8 * s2 + 0] * f, p[kb][8 * s2 + 1] * f); w.y = pk2(p[kb][8 * s2 + 2] * f, p[kb][8 * s2 + 3] * f);
;                     w.z = pk2(p[kb][8 * s2 + 4] * f, p[kb][8 * s2 + 5] * f); w.w = pk2(p[kb][8 * s2 + 6] * f, p[kb][8 * s2 + 7] * f);
;                     pa[kb][s2] = __builtin_bit_cast(bf16x8, w); } }
; #pragma unroll
;             for (int d = 0; d < 4; ++d)
; #pragma unroll
;                 for (int kb = 0; kb < 2; ++kb)
; #pragma unroll
;                     for (int s2 = 0; s2 < 2; ++s2) { const bf16x8 vb = *(const LAS bf16x8*)(vb_ + d * 32 * AV_ROWB + kb * 64 + s2 * 16); o[d] = __builtin_amdgcn_mfma_f32_32x32x16_bf16(pa[kb][s2], vb, o[d], 0, 0, 0); }
;             wdone = __all(R >= ATT_DONE_LOG2) != 0;
	v_log_f32_e32 v193, v193
	v_cndmask_b32_e32 v72, 0, v72, vcc
	v_cmp_lt_i32_e32 vcc, v194, v173
	s_or_b64 vcc, s[62:63], vcc
	v_sub_f32_e32 v71, v71, v193
	v_cndmask_b32_e32 v193, 0, v193, vcc
	v_sub_f32_e32 v71, v71, v192
	v_add_f32_e32 v192, v193, v192
	v_exp_f32_e32 v193, v70
	v_exp_f32_e32 v71, v71
	v_add_u32_e32 v194, 0x46, v175
	v_add_f32_e32 v193, 1.0, v193
	v_log_f32_e32 v193, v193
	v_cndmask_b32_e32 v71, 0, v71, vcc
	v_cmp_lt_i32_e32 vcc, v194, v173
	s_or_b64 vcc, s[62:63], vcc
	v_sub_f32_e32 v70, v70, v193
	v_cndmask_b32_e32 v193, 0, v193, vcc
	v_sub_f32_e32 v70, v70, v192
	v_add_f32_e32 v192, v193, v192
	v_exp_f32_e32 v193, v69
	v_exp_f32_e32 v70, v70
	v_add_u32_e32 v194, 0x45, v175
	v_add_f32_e32 v193, 1.0, v193
	v_log_f32_e32 v193, v193
	v_cndmask_b32_e32 v70, 0, v70, vcc
	v_cmp_lt_i32_e32 vcc, v194, v173
	s_or_b64 vcc, s[62:63], vcc
	v_sub_f32_e32 v69, v69, v193
	v_cndmask_b32_e32 v193, 0, v193, vcc
	v_sub_f32_e32 v69, v69, v192
	v_add_f32_e32 v192, v193, v192
	v_exp_f32_e32 v193, v68
	v_exp_f32_e32 v69, v69
	v_add_u32_e32 v194, 0x44, v175
	v_add_f32_e32 v193, 1.0, v193
	v_log_f32_e32 v193, v193
	v_cndmask_b32_e32 v69, 0, v69, vcc
	v_cmp_lt_i32_e32 vcc, v194, v173
	s_or_b64 vcc, s[62:63], vcc
	v_sub_f32_e32 v68, v68, v193
	v_cndmask_b32_e32 v193, 0, v193, vcc
	v_sub_f32_e32 v68, v68, v192
	v_add_f32_e32 v192, v193, v192
	v_exp_f32_e32 v193, v67
	v_exp_f32_e32 v68, v68
	v_add_u32_e32 v194, 0x43, v175
	v_add_f32_e32 v193, 1.0, v193
	v_log_f32_e32 v193, v193
	v_cndmask_b32_e32 v68, 0, v68, vcc
	v_cmp_lt_i32_e32 vcc, v194, v173
	s_or_b64 vcc, s[62:63], vcc
	v_sub_f32_e32 v67, v67, v193
	v_cndmask_b32_e32 v193, 0, v193, vcc
	v_sub_f32_e32 v67, v67, v192
	v_add_f32_e32 v192, v193, v192
	v_exp_f32_e32 v193, v66
	v_exp_f32_e32 v67, v67
	v_add_u32_e32 v194, 0x42, v175
	v_add_u32_e32 v175, 0x41, v175
	v_add_f32_e32 v193, 1.0, v193
	v_log_f32_e32 v193, v193
	v_cndmask_b32_e32 v67, 0, v67, vcc
	v_cmp_lt_i32_e32 vcc, v194, v173
	s_or_b64 vcc, s[62:63], vcc
	v_sub_f32_e32 v66, v66, v193
	v_cndmask_b32_e32 v193, 0, v193, vcc
	v_sub_f32_e32 v66, v66, v192
	v_add_f32_e32 v192, v193, v192
	v_exp_f32_e32 v193, v65
	v_exp_f32_e32 v66, v66
	v_add_f32_e32 v194, v169, v184
	v_add_f32_e32 v193, 1.0, v193
	v_log_f32_e32 v193, v193
	v_cndmask_b32_e32 v66, 0, v66, vcc
	v_cmp_lt_i32_e32 vcc, v175, v173
	s_or_b64 vcc, s[62:63], vcc
	v_sub_f32_e32 v65, v65, v193
	v_cndmask_b32_e32 v175, 0, v193, vcc
	v_sub_f32_e32 v65, v65, v192
	v_add_f32_e32 v175, v175, v192
	v_exp_f32_e32 v192, v64
	v_exp_f32_e32 v65, v65
	v_add_f32_e32 v192, 1.0, v192
	v_log_f32_e32 v192, v192
	v_cndmask_b32_e32 v65, 0, v65, vcc
	v_cmp_lt_i32_e32 vcc, v171, v173
	s_or_b64 vcc, s[62:63], vcc
	v_sub_f32_e32 v64, v64, v192
	v_cndmask_b32_e32 v171, 0, v192, vcc
	v_add_f32_e32 v171, v171, v175
	v_sub_f32_e32 v64, v64, v175
	ds_bpermute_b32 v175, v157, v171
	ds_bpermute_b32 v192, v157, v184
	v_exp_f32_e32 v64, v64
	s_waitcnt lgkmcnt(1)
	v_cndmask_b32_e64 v195, 0, v175, s[4:5]
	s_waitcnt lgkmcnt(0)
	v_add_f32_e32 v194, v194, v192
	v_add_f32_e32 v194, v195, v194
	v_exp_f32_e64 v194, -v194
	v_cndmask_b32_e32 v64, 0, v64, vcc
	v_cndmask_b32_e64 v193, 0, v192, s[4:5]
	v_add_f32_e32 v193, v169, v193
	v_mul_f32_e32 v64, v64, v194
	v_mul_f32_e32 v65, v65, v194
	v_cvt_pk_bf16_f32 v64, v64, v65
	v_mul_f32_e32 v65, v66, v194
	v_mul_f32_e32 v66, v67, v194
	v_cvt_pk_bf16_f32 v65, v65, v66
	v_mul_f32_e32 v66, v68, v194
	v_mul_f32_e32 v67, v69, v194
	v_cvt_pk_bf16_f32 v66, v66, v67
	v_mul_f32_e32 v67, v70, v194
	v_mul_f32_e32 v68, v71, v194
	v_exp_f32_e64 v193, -v193
	v_cvt_pk_bf16_f32 v67, v67, v68
	v_mul_f32_e32 v68, v72, v194
	v_mul_f32_e32 v69, v73, v194
	v_cvt_pk_bf16_f32 v68, v68, v69
	v_mul_f32_e32 v69, v74, v194
	v_mul_f32_e32 v70, v75, v194
	v_cvt_pk_bf16_f32 v69, v69, v70
	v_mul_f32_e32 v70, v76, v194
	v_mul_f32_e32 v71, v77, v194
	v_cvt_pk_bf16_f32 v70, v70, v71
	v_mul_f32_e32 v71, v78, v194
	v_mul_f32_e32 v72, v79, v194
	v_cvt_pk_bf16_f32 v71, v71, v72
	v_mul_f32_e32 v72, v193, v80
	v_mul_f32_e32 v73, v193, v81
	v_cvt_pk_bf16_f32 v76, v72, v73
	v_mul_f32_e32 v72, v193, v82
	v_mul_f32_e32 v73, v193, v83
	v_cvt_pk_bf16_f32 v77, v72, v73
	v_mul_f32_e32 v72, v193, v84
	v_mul_f32_e32 v73, v193, v85
	v_cvt_pk_bf16_f32 v78, v72, v73
	v_mul_f32_e32 v72, v193, v86
	v_mul_f32_e32 v73, v193, v87
	v_cvt_pk_bf16_f32 v79, v72, v73
	v_mul_f32_e32 v72, v193, v88
	v_mul_f32_e32 v73, v193, v89
	v_cvt_pk_bf16_f32 v72, v72, v73
	v_mul_f32_e32 v73, v193, v90
	v_mul_f32_e32 v74, v193, v91
	v_cvt_pk_bf16_f32 v73, v73, v74
	v_mul_f32_e32 v74, v193, v92
	v_mul_f32_e32 v75, v193, v93
	v_cvt_pk_bf16_f32 v74, v74, v75
	v_mul_f32_e32 v75, v193, v94
	v_mul_f32_e32 v80, v193, v95
	v_add_u32_e32 v88, s16, v191
	v_cvt_pk_bf16_f32 v75, v75, v80
	ds_read_b128 v[80:83], v88 offset:34816
	ds_read_b128 v[84:87], v88 offset:34832
	ds_read_b128 v[92:95], v88 offset:34880
	s_waitcnt lgkmcnt(2)
	v_mfma_f32_32x32x16_bf16 v[0:15], v[64:67], v[80:83], v[0:15]
	ds_read_b128 v[80:83], v88 offset:34896
	v_add_f32_e32 v171, v171, v175
	v_add_f32_e32 v175, v184, v192
	v_add_f32_e32 v171, v171, v175
	v_add_f32_e32 v169, v169, v171
	v_cmp_le_f32_e32 vcc, s72, v169
	s_cmp_eq_u64 vcc, exec
	s_waitcnt lgkmcnt(2)
	v_mfma_f32_32x32x16_bf16 v[0:15], v[68:71], v[84:87], v[0:15]
	ds_read_b128 v[84:87], v88 offset:39424
	s_cselect_b64 s[16:17], -1, 0
	s_waitcnt lgkmcnt(2)
	v_mfma_f32_32x32x16_bf16 v[0:15], v[76:79], v[92:95], v[0:15]
	ds_read_b128 v[92:95], v88 offset:39440
	s_waitcnt lgkmcnt(2)
	v_mfma_f32_32x32x16_bf16 v[0:15], v[72:75], v[80:83], v[0:15]
	ds_read_b128 v[80:83], v88 offset:39488
	s_waitcnt lgkmcnt(2)
	v_mfma_f32_32x32x16_bf16 v[48:63], v[64:67], v[84:87], v[48:63]
	ds_read_b128 v[84:87], v88 offset:39504
	s_waitcnt lgkmcnt(2)
	v_mfma_f32_32x32x16_bf16 v[48:63], v[68:71], v[92:95], v[48:63]
	ds_read_b128 v[92:95], v88 offset:44032
	s_waitcnt lgkmcnt(2)
	v_mfma_f32_32x32x16_bf16 v[48:63], v[76:79], v[80:83], v[48:63]
	ds_read_b128 v[80:83], v88 offset:44048
	s_waitcnt lgkmcnt(2)
	v_mfma_f32_32x32x16_bf16 v[48:63], v[72:75], v[84:87], v[48:63]
	ds_read_b128 v[84:87], v88 offset:44096
	s_waitcnt lgkmcnt(2)
	v_mfma_f32_32x32x16_bf16 v[32:47], v[64:67], v[92:95], v[32:47]
	ds_read_b128 v[92:95], v88 offset:44112
	s_waitcnt lgkmcnt(2)
	v_mfma_f32_32x32x16_bf16 v[32:47], v[68:71], v[80:83], v[32:47]
	ds_read_b128 v[80:83], v88 offset:48640
	s_waitcnt lgkmcnt(2)
	v_mfma_f32_32x32x16_bf16 v[32:47], v[76:79], v[84:87], v[32:47]
	ds_read_b128 v[84:87], v88 offset:48656
	s_waitcnt lgkmcnt(2)
	v_mfma_f32_32x32x16_bf16 v[32:47], v[72:75], v[92:95], v[32:47]
	ds_read_b128 v[92:95], v88 offset:48704
	s_waitcnt lgkmcnt(2)
	v_mfma_f32_32x32x16_bf16 v[16:31], v[64:67], v[80:83], v[16:31]
	ds_read_b128 v[80:83], v88 offset:48720
	s_waitcnt lgkmcnt(2)
	v_mfma_f32_32x32x16_bf16 v[16:31], v[68:71], v[84:87], v[16:31]
	s_waitcnt lgkmcnt(1)
	v_mfma_f32_32x32x16_bf16 v[16:31], v[76:79], v[92:95], v[16:31]
	s_waitcnt lgkmcnt(0)
	v_mfma_f32_32x32x16_bf16 v[16:31], v[72:75], v[80:83], v[16:31]
